# MLA attention: V-fragment LDS reads issued before K-fragment reads (PV no longer waits behind next tile's K reads), counted lgkmcnt adjusted; plus GEMM K-loop vmcnt(0) removal
# baseline (speedup 1.0000x reference)
; #define MFMA32(a, b, c) __builtin_amdgcn_mfma_f32_32x32x16_bf16((a), (b), (c), 0, 0, 0)
; #define PV_IDX(g) (((g) & 1) * 4 + PV_KS(g))
; template <int DQK, int DV, bool MLA>
; __device__ __forceinline__ void attn_pass(LAS unsigned char* lds, const bf16_t* Qrow, const bf16_t* K0, int pitchK, const bf16_t* KrB, const bf16_t* Vt0, int NT, int q0w,
;                                           f32x16 (&o)[DV / 32], float& l_out, int tid) {
;     ...
;             __builtin_amdgcn_s_setprio(1);
; #pragma unroll
;             for (int d0 = 0; d0 < ND; ++d0) { s0 = MFMA32(kf[2 * d0], q[d0], s0); s1 = MFMA32(kf[2 * d0 + 1], q[d0], s1); }
;             __builtin_amdgcn_s_setprio(0);
;             __builtin_amdgcn_sched_barrier(0);
;             if (t + 1 < NT) ATT_KLOAD((t + 1) & 3);
;             bf16x8 vf[8];
;             if (pend) {
; #pragma unroll
;                 for (int g = 0; g < 8; ++g) vf[PV_IDX(g)] = VFRAG(vp, PV_D(g), PV_KS(g));
;             }
.LBB0_70:
	s_setprio 1
	s_waitcnt lgkmcnt(0)
	v_mfma_f32_32x32x16_bf16 v[66:81], v[150:153], v[82:85], v[34:49]
	v_mfma_f32_32x32x16_bf16 v[50:65], v[146:149], v[82:85], v[34:49]
	v_mfma_f32_32x32x16_bf16 v[66:81], v[142:145], v[86:89], v[66:81]
	v_mfma_f32_32x32x16_bf16 v[50:65], v[138:141], v[86:89], v[50:65]
	v_mfma_f32_32x32x16_bf16 v[66:81], v[134:137], v[90:93], v[66:81]
	v_mfma_f32_32x32x16_bf16 v[50:65], v[130:133], v[90:93], v[50:65]
	v_mfma_f32_32x32x16_bf16 v[66:81], v[126:129], v[94:97], v[66:81]
	v_mfma_f32_32x32x16_bf16 v[50:65], v[122:125], v[94:97], v[50:65]
	v_mfma_f32_32x32x16_bf16 v[66:81], v[114:117], v[98:101], v[66:81]
	v_mfma_f32_32x32x16_bf16 v[50:65], v[110:113], v[98:101], v[50:65]
	v_mfma_f32_32x32x16_bf16 v[66:81], v[118:121], v[102:105], v[66:81]
	v_mfma_f32_32x32x16_bf16 v[50:65], v[106:109], v[102:105], v[50:65]
	s_setprio 0
	s_and_saveexec_b64 s[6:7], s[48:49]
	s_cbranch_execz .LBB0_74
	v_add_u32_e32 v170, v214, v244
	v_add_u32_e32 v174, v214, v251
	v_add_u32_e32 v182, v214, v250
	v_add_u32_e32 v190, v214, v249
	ds_read_b128 v[178:181], v170 offset:49152
	ds_read_b128 v[170:173], v170 offset:53248
	ds_read_b128 v[186:189], v174 offset:49152
	ds_read_b128 v[174:177], v174 offset:53248
	ds_read_b128 v[194:197], v182 offset:49152
	ds_read_b128 v[182:185], v182 offset:53248
	ds_read_b128 v[198:201], v190 offset:49152
	ds_read_b128 v[190:193], v190 offset:53248
.LBB0_74:
	s_or_b64 exec, exec, s[6:7]
	s_add_i32 s6, s57, 5
	s_and_b32 s6, s6, 3
	v_lshl_add_u32 v106, s6, 13, v246
	v_add_u32_e32 v108, v106, v244
	ds_read_b128 v[150:153], v108
	ds_read_b128 v[146:149], v108 offset:4096
	v_add_u32_e32 v108, v106, v251
	v_lshl_add_u32 v107, s6, 12, v247
	ds_read_b128 v[142:145], v108
	ds_read_b128 v[138:141], v108 offset:4096
	v_add_u32_e32 v108, v106, v250
	v_add_u32_e32 v106, v106, v249
	ds_read_b128 v[134:137], v108
	ds_read_b128 v[130:133], v108 offset:4096
	ds_read_b128 v[126:129], v106
	ds_read_b128 v[122:125], v106 offset:4096
	v_add_u32_e32 v106, v107, v245
	v_add_u32_e32 v118, v107, v248
	ds_read_b128 v[114:117], v106 offset:32768
	ds_read_b128 v[110:113], v106 offset:34816
	ds_read_b128 v[106:109], v118 offset:34816
	ds_read_b128 v[118:121], v118 offset:32768
; #define MFMA32(a, b, c) __builtin_amdgcn_mfma_f32_32x32x16_bf16((a), (b), (c), 0, 0, 0)
; __device__ __forceinline__ float max3f(float a, float b, float c) { float r; asm("v_max3_f32 %0, %1, %2, %3" : "=v"(r) : "v"(a), "v"(b), "v"(c)); return r; }
; __device__ __forceinline__ float xhalf_max(float v) { auto rr = __builtin_amdgcn_permlane32_swap(__float_as_uint(v), __float_as_uint(v), false, false); return __builtin_fmaxf(__uint_as_float(rr[0]), __uint_as_float(rr[1])); }
; #define PV_IDX(g) (((g) & 1) * 4 + PV_KS(g))
; template <int DQK, int DV, bool MLA>
; __device__ __forceinline__ void attn_pass(LAS unsigned char* lds, const bf16_t* Qrow, const bf16_t* K0, int pitchK, const bf16_t* KrB, const bf16_t* Vt0, int NT, int q0w,
;                                           f32x16 (&o)[DV / 32], float& l_out, int tid) {
;     ...
;             if (64 * t + 63 > q0w) {
;                 int hi_l = hi; asm volatile("" : "+v"(hi_l));
;                 const int qrow = q0w + r32, kb0 = 64 * t + 4 * hi_l;
; #pragma unroll
;                 for (int r = 0; r < 16; ++r) { const int kv = kb0 + (r & 3) + 8 * (r >> 2); if (kv > qrow) s0[r] = -INFINITY; if (kv + 32 > qrow) s1[r] = -INFINITY; }
;             }
;             float mx;
;             asm volatile("s_nop 11" : "+v"(s0), "+v"(s1));
;             {
;                 float a = max3f(s0[0], s0[1], s1[0]), b = max3f(s0[2], s0[3], s1[1]); a = max3f(a, s1[2], s1[3]);
; #pragma unroll
;                 for (int r = 4; r < 16; r += 4) { a = max3f(a, s0[r], s0[r + 1]); b = max3f(b, s0[r + 2], s0[r + 3]); a = max3f(a, s1[r], s1[r + 1]); b = max3f(b, s1[r + 2], s1[r + 3]); }
;                 mx = xhalf_max(__builtin_fmaxf(a, b)) - (MLA ? 0.f : m);
;             }
;             if (t == 0 || __any(mx > THR)) {
;                 if (pend) {
; #pragma unroll
;                     for (int g = 0; g < NG; ++g) {
;                         o[PV_D(g)] = MFMA32(vf[PV_IDX(g)], pf[PV_KS(g)], o[PV_D(g)]);
;                         if (NDV == 4 && g < 8) vf[PV_IDX(g)] = VFRAG(vp, PV_D(g) + 2, PV_KS(g));
;                     }
.LBB0_72:
	v_cmp_gt_i32_e32 vcc, s90, v202
	s_and_saveexec_b64 s[6:7], vcc
	s_cbranch_execz .LBB0_76
	v_mov_b32_e32 v214, v239
	s_nop 0
	v_lshl_add_u32 v214, v214, 2, s90
	v_subrev_u32_e32 v223, 31, v214
	v_subrev_u32_e32 v215, 63, v214
	v_cmp_le_i32_e32 vcc, v223, v252
	s_nop 1
	v_cndmask_b32_e32 v50, v220, v50, vcc
	v_cmp_lt_i32_e32 vcc, v215, v252
	s_nop 1
	v_cndmask_b32_e32 v67, v220, v67, vcc
	v_cmp_le_i32_e32 vcc, v215, v252
	v_subrev_u32_e32 v215, 30, v214
	s_nop 0
	v_cndmask_b32_e32 v66, v220, v66, vcc
	v_cmp_le_i32_e32 vcc, v215, v252
	v_subrev_u32_e32 v215, 61, v214
	s_nop 0
	v_cndmask_b32_e32 v51, v220, v51, vcc
	v_cmp_le_i32_e32 vcc, v215, v252
	v_subrev_u32_e32 v215, 29, v214
	s_nop 0
	v_cndmask_b32_e32 v68, v220, v68, vcc
	v_cmp_le_i32_e32 vcc, v215, v252
	v_subrev_u32_e32 v215, 60, v214
	s_nop 0
	v_cndmask_b32_e32 v52, v220, v52, vcc
	v_cmp_le_i32_e32 vcc, v215, v252
	v_subrev_u32_e32 v215, 28, v214
	s_nop 0
	v_cndmask_b32_e32 v69, v220, v69, vcc
	v_cmp_le_i32_e32 vcc, v215, v252
	v_subrev_u32_e32 v215, 55, v214
	s_nop 0
	v_cndmask_b32_e32 v53, v220, v53, vcc
	v_cmp_le_i32_e32 vcc, v215, v252
	v_subrev_u32_e32 v215, 23, v214
	s_nop 0
	v_cndmask_b32_e32 v70, v220, v70, vcc
	v_cmp_le_i32_e32 vcc, v215, v252
	v_subrev_u32_e32 v215, 54, v214
	s_nop 0
	v_cndmask_b32_e32 v54, v220, v54, vcc
	v_cmp_le_i32_e32 vcc, v215, v252
	v_subrev_u32_e32 v215, 22, v214
	s_nop 0
	v_cndmask_b32_e32 v71, v220, v71, vcc
	v_cmp_le_i32_e32 vcc, v215, v252
	v_subrev_u32_e32 v215, 53, v214
	s_nop 0
	v_cndmask_b32_e32 v55, v220, v55, vcc
	v_cmp_le_i32_e32 vcc, v215, v252
	v_subrev_u32_e32 v215, 21, v214
	s_nop 0
	v_cndmask_b32_e32 v72, v220, v72, vcc
	v_cmp_le_i32_e32 vcc, v215, v252
	v_subrev_u32_e32 v215, 52, v214
	s_nop 0
	v_cndmask_b32_e32 v56, v220, v56, vcc
	v_cmp_le_i32_e32 vcc, v215, v252
	v_subrev_u32_e32 v215, 20, v214
	s_nop 0
	v_cndmask_b32_e32 v73, v220, v73, vcc
	v_cmp_le_i32_e32 vcc, v215, v252
	v_subrev_u32_e32 v215, 47, v214
	s_nop 0
	v_cndmask_b32_e32 v57, v220, v57, vcc
	v_cmp_le_i32_e32 vcc, v215, v252
	v_add_u32_e32 v215, -15, v214
	s_nop 0
	v_cndmask_b32_e32 v74, v220, v74, vcc
	v_cmp_le_i32_e32 vcc, v215, v252
	v_subrev_u32_e32 v215, 46, v214
	s_nop 0
	v_cndmask_b32_e32 v58, v220, v58, vcc
	v_cmp_le_i32_e32 vcc, v215, v252
	v_add_u32_e32 v215, -14, v214
	s_nop 0
	v_cndmask_b32_e32 v75, v220, v75, vcc
	v_cmp_le_i32_e32 vcc, v215, v252
	v_subrev_u32_e32 v215, 45, v214
	s_nop 0
	v_cndmask_b32_e32 v59, v220, v59, vcc
	v_cmp_le_i32_e32 vcc, v215, v252
	v_add_u32_e32 v215, -13, v214
	s_nop 0
	v_cndmask_b32_e32 v76, v220, v76, vcc
	v_cmp_le_i32_e32 vcc, v215, v252
	v_subrev_u32_e32 v215, 44, v214
	s_nop 0
	v_cndmask_b32_e32 v60, v220, v60, vcc
	v_cmp_le_i32_e32 vcc, v215, v252
	v_add_u32_e32 v215, -12, v214
	s_nop 0
	v_cndmask_b32_e32 v77, v220, v77, vcc
	v_cmp_le_i32_e32 vcc, v215, v252
	v_subrev_u32_e32 v215, 39, v214
	s_nop 0
	v_cndmask_b32_e32 v61, v220, v61, vcc
	v_cmp_le_i32_e32 vcc, v215, v252
	v_add_u32_e32 v215, -7, v214
	s_nop 0
	v_cndmask_b32_e32 v78, v220, v78, vcc
	v_cmp_le_i32_e32 vcc, v215, v252
	v_subrev_u32_e32 v215, 38, v214
	s_nop 0
	v_cndmask_b32_e32 v62, v220, v62, vcc
	v_cmp_le_i32_e32 vcc, v215, v252
	v_add_u32_e32 v215, -6, v214
	s_nop 0
	v_cndmask_b32_e32 v79, v220, v79, vcc
	v_cmp_le_i32_e32 vcc, v215, v252
	v_subrev_u32_e32 v215, 37, v214
	s_nop 0
	v_cndmask_b32_e32 v63, v220, v63, vcc
	v_cmp_le_i32_e32 vcc, v215, v252
	v_add_u32_e32 v215, -5, v214
	s_nop 0
	v_cndmask_b32_e32 v80, v220, v80, vcc
	v_cmp_le_i32_e32 vcc, v215, v252
	v_subrev_u32_e32 v215, 36, v214
	v_add_u32_e32 v214, -4, v214
	v_cndmask_b32_e32 v64, v220, v64, vcc
	v_cmp_le_i32_e32 vcc, v215, v252
	s_nop 1
	v_cndmask_b32_e32 v81, v220, v81, vcc
	v_cmp_le_i32_e32 vcc, v214, v252
	s_nop 1
	v_cndmask_b32_e32 v65, v220, v65, vcc
.LBB0_76:
	s_or_b64 exec, exec, s[6:7]
	s_nop 11
	s_nop 0
	v_max3_f32 v214, v66, v67, v50
	v_max3_f32 v215, v68, v69, v51
	s_nop 0
	v_max3_f32 v214, v214, v52, v53
	v_max3_f32 v215, v215, v72, v73
	s_nop 0
	v_max3_f32 v214, v214, v70, v71
	v_max3_f32 v215, v215, v56, v57
	s_nop 0
	v_max3_f32 v214, v214, v54, v55
	v_max3_f32 v215, v215, v76, v77
	s_nop 0
	v_max3_f32 v214, v214, v74, v75
	v_max3_f32 v215, v215, v60, v61
	s_nop 0
	v_max3_f32 v214, v214, v58, v59
	v_max3_f32 v215, v215, v80, v81
	s_nop 0
	v_max3_f32 v214, v214, v78, v79
	v_max3_f32 v215, v215, v64, v65
	s_nop 0
	v_max3_f32 v214, v214, v62, v63
	v_max_f32_e32 v215, v215, v215
	v_max_f32_e32 v214, v214, v214
	v_max_f32_e32 v214, v214, v215
	v_mov_b32_e32 v215, v214
	s_nop 1
	v_permlane32_swap_b32_e32 v214, v215
	v_max_f32_e32 v215, v215, v215
	v_max_f32_e32 v214, v214, v214
	v_max_f32_e32 v214, v214, v215
	v_cmp_lt_f32_e32 vcc, s66, v214
	s_cbranch_vccz .LBB0_80
	s_and_saveexec_b64 s[6:7], s[48:49]
	s_cbranch_execz .LBB0_79
	s_waitcnt lgkmcnt(15)
	v_mfma_f32_32x32x16_bf16 v[18:33], v[178:181], v[158:161], v[18:33]
	s_waitcnt lgkmcnt(15)
	v_mfma_f32_32x32x16_bf16 v[2:17], v[170:173], v[158:161], v[2:17]
	s_waitcnt lgkmcnt(15)
	v_mfma_f32_32x32x16_bf16 v[18:33], v[186:189], v[162:165], v[18:33]
	s_waitcnt lgkmcnt(15)
	v_mfma_f32_32x32x16_bf16 v[2:17], v[174:177], v[162:165], v[2:17]
	s_waitcnt lgkmcnt(15)
	v_mfma_f32_32x32x16_bf16 v[18:33], v[194:197], v[166:169], v[18:33]
	s_waitcnt lgkmcnt(14)
	v_mfma_f32_32x32x16_bf16 v[2:17], v[182:185], v[166:169], v[2:17]
	s_waitcnt lgkmcnt(13)
	v_mfma_f32_32x32x16_bf16 v[18:33], v[198:201], v[154:157], v[18:33]
	s_waitcnt lgkmcnt(12)
	v_mfma_f32_32x32x16_bf16 v[2:17], v[190:193], v[154:157], v[2:17]

; __device__ __forceinline__ unsigned cvtpk(float lo, float hi) { const f32x2 v = {lo, hi}; const bf16x2_t b = __builtin_convertvector(v, bf16x2_t); return __builtin_bit_cast(unsigned, b); }
; #define MFMA32(a, b, c) __builtin_amdgcn_mfma_f32_32x32x16_bf16((a), (b), (c), 0, 0, 0)
; template <int DQK, int DV, bool MLA>
; __device__ __forceinline__ void attn_pass(LAS unsigned char* lds, const bf16_t* Qrow, const bf16_t* K0, int pitchK, const bf16_t* KrB, const bf16_t* Vt0, int NT, int q0w,
;                                           f32x16 (&o)[DV / 32], float& l_out, int tid) {
;     ...
;             float ps = 0.f;
;             u32x4 pw[4];
;             float ps1 = 0.f;
;             if (pend) {
; #pragma unroll
;                 for (int g = 0; g <= NG; ++g) {
;                     if (g < NG) {
;                         o[PV_D(g)] = MFMA32(vf[PV_IDX(g)], pf[PV_KS(g)], o[PV_D(g)]);
;                         if (NDV == 4 && g < 8) vf[PV_IDX(g)] = VFRAG(vp, PV_D(g) + 2, PV_KS(g));
; #pragma unroll
;                         for (int e = g * EPG; e < (g + 1) * EPG; ++e) { if (e < 16) s0[e] = __builtin_amdgcn_exp2f(MLA ? s0[e] : s0[e] - m); else s1[e - 16] = __builtin_amdgcn_exp2f(MLA ? s1[e - 16] : s1[e - 16] - m); }
;                     }
;                     if (g > 0) {
; #pragma unroll
;                         for (int e = (g - 1) * EPG; e < g * EPG; ++e) {
;                             const float v = e < 16 ? s0[e] : s1[e - 16];
;                             if (e & 1) ps1 += v; else ps += v;
;                             if (e & 1) { const int j = e >> 1; pw[j >> 2][j & 3] = e < 16 ? cvtpk(s0[e - 1], s0[e]) : cvtpk(s1[e - 17], s1[e - 16]); }
;                         }
;                     }
;                     __builtin_amdgcn_sched_barrier(0);
;                 }
;             } else {
;                 float m2 = MLA ? 0.f : m; asm volatile("" : "+v"(m2));
; #pragma unroll
;                 for (int e = 0; e < 32; ++e) {
;                     if (e < 16) { s0[e] = __builtin_amdgcn_exp2f(MLA ? s0[e] + m2 : s0[e] - m2); ps += s0[e]; } else { s1[e - 16] = __builtin_amdgcn_exp2f(MLA ? s1[e - 16] + m2 : s1[e - 16] - m2); ps += s1[e - 16]; }
;                     if (e & 1) { const int j = e >> 1; pw[j >> 2][j & 3] = e < 16 ? cvtpk(s0[e - 1], s0[e]) : cvtpk(s1[e - 17], s1[e - 16]); }
;                 }
;             }
;             l += ps + ps1;
.LBB0_82:
	s_or_saveexec_b64 s[6:7], s[6:7]
	v_mov_b32_e32 v215, 0
	s_xor_b64 exec, exec, s[6:7]
	s_cbranch_execz .LBB0_84
	s_waitcnt lgkmcnt(15)
	v_mfma_f32_32x32x16_bf16 v[18:33], v[178:181], v[158:161], v[18:33]
	v_exp_f32_e32 v66, v66
	v_exp_f32_e32 v67, v67
	v_exp_f32_e32 v68, v68
	v_exp_f32_e32 v69, v69
	s_waitcnt lgkmcnt(15)
	v_mfma_f32_32x32x16_bf16 v[2:17], v[170:173], v[158:161], v[2:17]
	v_cvt_pk_bf16_f32 v158, v66, v67
	v_cvt_pk_bf16_f32 v159, v68, v69
	v_exp_f32_e32 v70, v70
	v_exp_f32_e32 v71, v71
	v_exp_f32_e32 v72, v72
	v_exp_f32_e32 v73, v73
	s_waitcnt lgkmcnt(15)
	v_mfma_f32_32x32x16_bf16 v[18:33], v[186:189], v[162:165], v[18:33]
	v_cvt_pk_bf16_f32 v160, v70, v71
	v_cvt_pk_bf16_f32 v161, v72, v73
	v_exp_f32_e32 v74, v74
	v_exp_f32_e32 v75, v75
	v_exp_f32_e32 v76, v76
	v_exp_f32_e32 v77, v77
	s_waitcnt lgkmcnt(15)
	v_mfma_f32_32x32x16_bf16 v[2:17], v[174:177], v[162:165], v[2:17]
	v_add_f32_e64 v66, v66, 0
	v_add_f32_e64 v67, v67, 0
	v_cvt_pk_bf16_f32 v162, v74, v75
	v_add_f32_e64 v66, v68, v66
	v_add_f32_e64 v67, v69, v67
	v_cvt_pk_bf16_f32 v163, v76, v77
	v_pk_add_f32 v[66:67], v[70:71], v[66:67]
	v_exp_f32_e32 v78, v78
	v_pk_add_f32 v[66:67], v[72:73], v[66:67]
	v_exp_f32_e32 v79, v79
	v_exp_f32_e32 v80, v80
	v_exp_f32_e32 v81, v81
	v_pk_add_f32 v[66:67], v[74:75], v[66:67]
	s_waitcnt lgkmcnt(15)
	v_mfma_f32_32x32x16_bf16 v[18:33], v[194:197], v[166:169], v[18:33]
	v_cvt_pk_bf16_f32 v164, v78, v79
	v_cvt_pk_bf16_f32 v165, v80, v81
	v_exp_f32_e32 v50, v50
	v_exp_f32_e32 v51, v51
	v_exp_f32_e32 v52, v52
	v_exp_f32_e32 v53, v53
	s_waitcnt lgkmcnt(14)
	v_mfma_f32_32x32x16_bf16 v[2:17], v[182:185], v[166:169], v[2:17]
	v_cvt_pk_bf16_f32 v166, v50, v51
	v_cvt_pk_bf16_f32 v167, v52, v53
	v_exp_f32_e32 v54, v54
	v_exp_f32_e32 v55, v55
	v_exp_f32_e32 v56, v56
	v_exp_f32_e32 v57, v57
	s_waitcnt lgkmcnt(13)
	v_mfma_f32_32x32x16_bf16 v[18:33], v[198:201], v[154:157], v[18:33]
	v_cvt_pk_bf16_f32 v168, v54, v55
	v_cvt_pk_bf16_f32 v169, v56, v57
	v_exp_f32_e32 v58, v58
	v_exp_f32_e32 v59, v59
	v_exp_f32_e32 v60, v60
	v_exp_f32_e32 v61, v61
	s_waitcnt lgkmcnt(12)
	v_mfma_f32_32x32x16_bf16 v[2:17], v[190:193], v[154:157], v[2:17]
	v_cvt_pk_bf16_f32 v154, v58, v59
	v_cvt_pk_bf16_f32 v155, v60, v61
	v_exp_f32_e32 v62, v62
	v_exp_f32_e32 v63, v63
	v_exp_f32_e32 v64, v64
	v_exp_f32_e32 v65, v65
	v_pk_add_f32 v[66:67], v[76:77], v[66:67]
	v_cvt_pk_bf16_f32 v156, v62, v63
	v_pk_add_f32 v[66:67], v[78:79], v[66:67]
	v_cvt_pk_bf16_f32 v157, v64, v65
	v_pk_add_f32 v[66:67], v[80:81], v[66:67]
	s_nop 0
	v_pk_add_f32 v[50:51], v[50:51], v[66:67]
	s_nop 0
	v_pk_add_f32 v[50:51], v[52:53], v[50:51]
	s_nop 0
	v_pk_add_f32 v[50:51], v[54:55], v[50:51]
	s_nop 0
	v_pk_add_f32 v[50:51], v[56:57], v[50:51]
	s_nop 0
	v_pk_add_f32 v[50:51], v[58:59], v[50:51]
	s_nop 0
	v_pk_add_f32 v[50:51], v[60:61], v[50:51]
	s_nop 0
	v_pk_add_f32 v[50:51], v[62:63], v[50:51]
	s_nop 0
	v_pk_add_f32 v[214:215], v[64:65], v[50:51]
